# xa_pass (x @ w_a1) moved from VALU f32 FMA to f32 matrix cores v_mfma_f32_16x16x4_f32 (f32 operands, f32 accumulate, bf16 x widened exactly), on top of the dsa_topk changes
# speedup vs baseline: 1.0120x; 1.0028x over previous
; __device__ __forceinline__ float bf2f(unsigned short b) { return __uint_as_float(((unsigned)b) << 16); }
; #define PF(i) ((const float*)ldp(lds, (i)))
; __device__ __forceinline__ void xa_pass(const bf16_t* srcb, const float* wa1, float* xa, int widk) {
;     ...
;     for (int r0 = gw * 4; r0 < T; r0 += NGW * 4) {
;         f32x4 acc[4][4];
; #pragma unroll
;         for (int rr = 0; rr < 4; ++rr)
; #pragma unroll
;             for (int qd = 0; qd < 4; ++qd) acc[rr][qd] = (f32x4){0.f, 0.f, 0.f, 0.f};
; #pragma unroll 2
;         for (int i = 0; i < 32; ++i) { const int cc = lane + 64 * i; const f32x4* w = (const f32x4*)(wa1 + (size_t)cc * 16);
;             const f32x4 w0 = w[0], w1 = w[1], w2 = w[2], w3 = w[3];
; #pragma unroll
;             for (int rr = 0; rr < 4; ++rr) { const float xv = bf2f(srcb[(size_t)(r0 + rr) * D + cc]);
;                 acc[rr][0] += w0 * xv; acc[rr][1] += w1 * xv; acc[rr][2] += w2 * xv; acc[rr][3] += w3 * xv; } }
; __global__ void __launch_bounds__(512, 2) mega_fwd(Params P) {
;     ...
;         const int kind = layer % 3, jl = layer / 3;
;         const float* xsrc = (layer == 0) ? PF(0) : XF;
;         if (kind != 1) {
;             if (kind == 0) for (int rep = 0; rep < REPN(21); ++rep) xa_pass(XB, PF(3) + (size_t)jl * D * 16, XA, widk);
.LBB0_260:
	s_cmp_lg_u32 s2, 3
	s_cselect_b64 s[0:1], -1, 0
	v_writelane_b32 v255, s0, 38
	s_cmp_eq_u32 s2, 3
	s_nop 0
	v_writelane_b32 v255, s1, 39
	s_cselect_b64 s[0:1], -1, 0
	v_writelane_b32 v255, s0, 40
	s_nop 1
	v_writelane_b32 v255, s1, 41
	s_and_b64 s[0:1], s[0:1], exec
	s_mov_b32 s0, s2
	s_cselect_b32 s26, 0, s2
	v_writelane_b32 v255, s0, 42
	s_cmp_lg_u32 s26, 1
	s_nop 0
	v_writelane_b32 v255, s1, 43
	s_cselect_b64 s[0:1], -1, 0
	s_cmp_eq_u32 s26, 1
	v_writelane_b32 v255, s0, 44
	s_cselect_b64 s[10:11], -1, 0
	s_and_b64 vcc, exec, s[10:11]
	v_writelane_b32 v255, s1, 45
	s_cbranch_vccnz .LBB0_345
	s_cmp_eq_u32 s26, 0
	s_cselect_b64 s[12:13], -1, 0
	s_cmp_lg_u32 s26, 0
	s_movk_i32 s27, 0x1100
	s_cbranch_scc1 .LBB0_276
	v_readlane_b32 s0, v252, 48
	v_mbcnt_lo_u32_b32 v0, -1, 0
	v_mbcnt_hi_u32_b32 v0, -1, v0
	v_readlane_b32 s2, v255, 40
	v_readlane_b32 s3, v255, 41
	v_readlane_b32 s8, v255, 14
	v_readlane_b32 s9, v255, 15
	v_readlane_b32 s16, v253, 37
	v_readlane_b32 s17, v253, 38
	s_waitcnt lgkmcnt(0)
	s_nop 3
	s_cmp_gt_u32 s0, 3
	s_cbranch_scc1 .LBB0_275
	s_and_b64 s[2:3], s[2:3], exec
	s_cselect_b32 s20, 0x20000, 0
	s_add_u32 s8, s8, s20
	s_addc_u32 s9, s9, 0
	s_sub_u32 s8, s8, 0x1030
	s_subb_u32 s9, s9, 0
	s_add_u32 s4, s86, 0x8000000
	s_addc_u32 s5, s87, 0
	s_lshl_b32 s14, s33, 2
	s_add_i32 s14, s14, s0
	s_lshl_b32 s15, s41, 2
	v_and_b32_e32 v2, 15, v0
	v_lshrrev_b32_e32 v3, 4, v0
	v_lshlrev_b32_e32 v4, 9, v3
	v_lshl_add_u32 v4, v2, 2, v4
	v_lshlrev_b32_e32 v5, 4, v3
	v_lshl_add_u32 v5, v2, 12, v5
	v_lshlrev_b32_e32 v72, 8, v3
	v_lshl_add_u32 v72, v2, 2, v72
.Lxa_blk:
	s_cmp_ge_u32 s14, 0x400
	s_cbranch_scc1 .LBB0_275
	s_lshl_b32 s18, s14, 16
	v_add_u32_e32 v6, s18, v5
	v_mov_b32_e32 v7, v4
	v_mov_b32_e32 v8, 0
	v_mov_b32_e32 v9, 0
	v_mov_b32_e32 v10, 0
	v_mov_b32_e32 v11, 0
	v_mov_b32_e32 v12, 0
	v_mov_b32_e32 v13, 0
	v_mov_b32_e32 v14, 0
	v_mov_b32_e32 v15, 0
	global_load_dwordx4 v[16:19], v6, s[4:5]
	global_load_dword v20, v7, s[8:9]
	global_load_dword v21, v7, s[8:9] offset:64
	global_load_dword v22, v7, s[8:9] offset:128
	global_load_dword v23, v7, s[8:9] offset:192
	global_load_dword v24, v7, s[8:9] offset:256
	global_load_dword v25, v7, s[8:9] offset:320
	global_load_dword v26, v7, s[8:9] offset:384
	global_load_dword v27, v7, s[8:9] offset:448
	v_add_u32_e32 v7, 0x800, v7
	global_load_dwordx4 v[28:31], v6, s[4:5] offset:64
	global_load_dword v32, v7, s[8:9]
	global_load_dword v33, v7, s[8:9] offset:64
	global_load_dword v34, v7, s[8:9] offset:128
	global_load_dword v35, v7, s[8:9] offset:192
	global_load_dword v36, v7, s[8:9] offset:256
	global_load_dword v37, v7, s[8:9] offset:320
	global_load_dword v38, v7, s[8:9] offset:384
	global_load_dword v39, v7, s[8:9] offset:448
	v_add_u32_e32 v7, 0x800, v7
	global_load_dwordx4 v[40:43], v6, s[4:5] offset:128
	global_load_dword v44, v7, s[8:9]
	global_load_dword v45, v7, s[8:9] offset:64
	global_load_dword v46, v7, s[8:9] offset:128
	global_load_dword v47, v7, s[8:9] offset:192
	global_load_dword v48, v7, s[8:9] offset:256
	global_load_dword v49, v7, s[8:9] offset:320
	global_load_dword v50, v7, s[8:9] offset:384
	global_load_dword v51, v7, s[8:9] offset:448
	v_add_u32_e32 v7, 0x800, v7
	global_load_dwordx4 v[52:55], v6, s[4:5] offset:192
	global_load_dword v56, v7, s[8:9]
	global_load_dword v57, v7, s[8:9] offset:64
	global_load_dword v58, v7, s[8:9] offset:128
	global_load_dword v59, v7, s[8:9] offset:192
	global_load_dword v60, v7, s[8:9] offset:256
	global_load_dword v61, v7, s[8:9] offset:320
	global_load_dword v62, v7, s[8:9] offset:384
	global_load_dword v63, v7, s[8:9] offset:448
	v_add_u32_e32 v7, 0x800, v7
	s_mov_b32 s19, 0
.Lxa_loop:
	s_waitcnt vmcnt(27)
	v_lshlrev_b32_e32 v64, 16, v16
	v_and_b32_e32 v65, 0xffff0000, v16
	v_lshlrev_b32_e32 v66, 16, v17
	v_and_b32_e32 v67, 0xffff0000, v17
	v_lshlrev_b32_e32 v68, 16, v18
	v_and_b32_e32 v69, 0xffff0000, v18
	v_lshlrev_b32_e32 v70, 16, v19
	v_and_b32_e32 v71, 0xffff0000, v19
	v_mfma_f32_16x16x4_f32 v[8:11], v64, v20, v[8:11]
	v_mfma_f32_16x16x4_f32 v[12:15], v65, v21, v[12:15]
	v_mfma_f32_16x16x4_f32 v[8:11], v66, v22, v[8:11]
	v_mfma_f32_16x16x4_f32 v[12:15], v67, v23, v[12:15]
	v_mfma_f32_16x16x4_f32 v[8:11], v68, v24, v[8:11]
	v_mfma_f32_16x16x4_f32 v[12:15], v69, v25, v[12:15]
	v_mfma_f32_16x16x4_f32 v[8:11], v70, v26, v[8:11]
	v_mfma_f32_16x16x4_f32 v[12:15], v71, v27, v[12:15]
	global_load_dwordx4 v[16:19], v6, s[4:5] offset:256
	global_load_dword v20, v7, s[8:9]
	global_load_dword v21, v7, s[8:9] offset:64
	global_load_dword v22, v7, s[8:9] offset:128
	global_load_dword v23, v7, s[8:9] offset:192
	global_load_dword v24, v7, s[8:9] offset:256
	global_load_dword v25, v7, s[8:9] offset:320
	global_load_dword v26, v7, s[8:9] offset:384
	global_load_dword v27, v7, s[8:9] offset:448
	v_add_u32_e32 v7, 0x800, v7
	s_waitcnt vmcnt(27)
	v_lshlrev_b32_e32 v64, 16, v28
	v_and_b32_e32 v65, 0xffff0000, v28
	v_lshlrev_b32_e32 v66, 16, v29
	v_and_b32_e32 v67, 0xffff0000, v29
	v_lshlrev_b32_e32 v68, 16, v30
	v_and_b32_e32 v69, 0xffff0000, v30
	v_lshlrev_b32_e32 v70, 16, v31
	v_and_b32_e32 v71, 0xffff0000, v31
	v_mfma_f32_16x16x4_f32 v[8:11], v64, v32, v[8:11]
	v_mfma_f32_16x16x4_f32 v[12:15], v65, v33, v[12:15]
	v_mfma_f32_16x16x4_f32 v[8:11], v66, v34, v[8:11]
	v_mfma_f32_16x16x4_f32 v[12:15], v67, v35, v[12:15]
	v_mfma_f32_16x16x4_f32 v[8:11], v68, v36, v[8:11]
	v_mfma_f32_16x16x4_f32 v[12:15], v69, v37, v[12:15]
	v_mfma_f32_16x16x4_f32 v[8:11], v70, v38, v[8:11]
	v_mfma_f32_16x16x4_f32 v[12:15], v71, v39, v[12:15]
	global_load_dwordx4 v[28:31], v6, s[4:5] offset:320
	global_load_dword v32, v7, s[8:9]
	global_load_dword v33, v7, s[8:9] offset:64
	global_load_dword v34, v7, s[8:9] offset:128
	global_load_dword v35, v7, s[8:9] offset:192
	global_load_dword v36, v7, s[8:9] offset:256
	global_load_dword v37, v7, s[8:9] offset:320
	global_load_dword v38, v7, s[8:9] offset:384
	global_load_dword v39, v7, s[8:9] offset:448
	v_add_u32_e32 v7, 0x800, v7
	s_waitcnt vmcnt(27)
; __device__ __forceinline__ float bf2f(unsigned short b) { return __uint_as_float(((unsigned)b) << 16); }
; __device__ __forceinline__ float shx(float v, int m, int lane) { return __int_as_float(__builtin_amdgcn_ds_bpermute((lane ^ m) << 2, __float_as_int(v))); }
; __device__ __forceinline__ void xa_pass(const bf16_t* srcb, const float* wa1, float* xa, int widk) {
;     ...
; #pragma unroll 2
;         for (int i = 0; i < 32; ++i) { const int cc = lane + 64 * i; const f32x4* w = (const f32x4*)(wa1 + (size_t)cc * 16);
;             const f32x4 w0 = w[0], w1 = w[1], w2 = w[2], w3 = w[3];
; #pragma unroll
;             for (int rr = 0; rr < 4; ++rr) { const float xv = bf2f(srcb[(size_t)(r0 + rr) * D + cc]);
;                 acc[rr][0] += w0 * xv; acc[rr][1] += w1 * xv; acc[rr][2] += w2 * xv; acc[rr][3] += w3 * xv; } }
;         const bool b5 = (lane & 32) != 0, b4 = (lane & 16) != 0, b3 = (lane & 8) != 0, b2 = (lane & 4) != 0;
;         const int idx = (b5 ? 8 : 0) + (b4 ? 4 : 0) + (b3 ? 2 : 0) + (b2 ? 1 : 0);
; #pragma unroll
;         for (int rr = 0; rr < 4; ++rr) {
;             float k8[8], k4[4], k2[2];
; #pragma unroll
;             for (int j = 0; j < 8; ++j) { const float lo = acc[rr][j >> 2][j & 3], hi = acc[rr][2 + (j >> 2)][j & 3]; k8[j] = (b5 ? hi : lo) + shx(b5 ? lo : hi, 32, lane); }
; #pragma unroll
;             for (int j = 0; j < 4; ++j) k4[j] = (b4 ? k8[j + 4] : k8[j]) + shx(b4 ? k8[j] : k8[j + 4], 16, lane);
; #pragma unroll
;             for (int j = 0; j < 2; ++j) k2[j] = (b3 ? k4[j + 2] : k4[j]) + shx(b3 ? k4[j] : k4[j + 2], 8, lane);
;             float k1 = (b2 ? k2[1] : k2[0]) + shx(b2 ? k2[0] : k2[1], 4, lane);
;             k1 += shx(k1, 2, lane); k1 += shx(k1, 1, lane);
;             if ((lane & 3) == 0) xa[(size_t)(r0 + rr) * 16 + idx] = k1;
	v_lshlrev_b32_e32 v64, 16, v40
	v_and_b32_e32 v65, 0xffff0000, v40
	v_lshlrev_b32_e32 v66, 16, v41
	v_and_b32_e32 v67, 0xffff0000, v41
	v_lshlrev_b32_e32 v68, 16, v42
	v_and_b32_e32 v69, 0xffff0000, v42
	v_lshlrev_b32_e32 v70, 16, v43
	v_and_b32_e32 v71, 0xffff0000, v43
	v_mfma_f32_16x16x4_f32 v[8:11], v64, v44, v[8:11]
	v_mfma_f32_16x16x4_f32 v[12:15], v65, v45, v[12:15]
	v_mfma_f32_16x16x4_f32 v[8:11], v66, v46, v[8:11]
	v_mfma_f32_16x16x4_f32 v[12:15], v67, v47, v[12:15]
	v_mfma_f32_16x16x4_f32 v[8:11], v68, v48, v[8:11]
	v_mfma_f32_16x16x4_f32 v[12:15], v69, v49, v[12:15]
	v_mfma_f32_16x16x4_f32 v[8:11], v70, v50, v[8:11]
	v_mfma_f32_16x16x4_f32 v[12:15], v71, v51, v[12:15]
	global_load_dwordx4 v[40:43], v6, s[4:5] offset:384
	global_load_dword v44, v7, s[8:9]
	global_load_dword v45, v7, s[8:9] offset:64
	global_load_dword v46, v7, s[8:9] offset:128
	global_load_dword v47, v7, s[8:9] offset:192
	global_load_dword v48, v7, s[8:9] offset:256
	global_load_dword v49, v7, s[8:9] offset:320
	global_load_dword v50, v7, s[8:9] offset:384
	global_load_dword v51, v7, s[8:9] offset:448
	v_add_u32_e32 v7, 0x800, v7
	s_waitcnt vmcnt(27)
	v_lshlrev_b32_e32 v64, 16, v52
	v_and_b32_e32 v65, 0xffff0000, v52
	v_lshlrev_b32_e32 v66, 16, v53
	v_and_b32_e32 v67, 0xffff0000, v53
	v_lshlrev_b32_e32 v68, 16, v54
	v_and_b32_e32 v69, 0xffff0000, v54
	v_lshlrev_b32_e32 v70, 16, v55
	v_and_b32_e32 v71, 0xffff0000, v55
	v_mfma_f32_16x16x4_f32 v[8:11], v64, v56, v[8:11]
	v_mfma_f32_16x16x4_f32 v[12:15], v65, v57, v[12:15]
	v_mfma_f32_16x16x4_f32 v[8:11], v66, v58, v[8:11]
	v_mfma_f32_16x16x4_f32 v[12:15], v67, v59, v[12:15]
	v_mfma_f32_16x16x4_f32 v[8:11], v68, v60, v[8:11]
	v_mfma_f32_16x16x4_f32 v[12:15], v69, v61, v[12:15]
	v_mfma_f32_16x16x4_f32 v[8:11], v70, v62, v[8:11]
	v_mfma_f32_16x16x4_f32 v[12:15], v71, v63, v[12:15]
	global_load_dwordx4 v[52:55], v6, s[4:5] offset:448
	global_load_dword v56, v7, s[8:9]
	global_load_dword v57, v7, s[8:9] offset:64
	global_load_dword v58, v7, s[8:9] offset:128
	global_load_dword v59, v7, s[8:9] offset:192
	global_load_dword v60, v7, s[8:9] offset:256
	global_load_dword v61, v7, s[8:9] offset:320
	global_load_dword v62, v7, s[8:9] offset:384
	global_load_dword v63, v7, s[8:9] offset:448
	v_add_u32_e32 v7, 0x800, v7
	v_add_u32_e32 v6, 0x100, v6
	s_add_i32 s19, s19, 1
	s_cmp_lt_u32 s19, 15
	s_cbranch_scc1 .Lxa_loop
	s_waitcnt vmcnt(27)
	v_lshlrev_b32_e32 v64, 16, v16
	v_and_b32_e32 v65, 0xffff0000, v16
	v_lshlrev_b32_e32 v66, 16, v17
	v_and_b32_e32 v67, 0xffff0000, v17
	v_lshlrev_b32_e32 v68, 16, v18
	v_and_b32_e32 v69, 0xffff0000, v18
	v_lshlrev_b32_e32 v70, 16, v19
	v_and_b32_e32 v71, 0xffff0000, v19
	v_mfma_f32_16x16x4_f32 v[8:11], v64, v20, v[8:11]
	v_mfma_f32_16x16x4_f32 v[12:15], v65, v21, v[12:15]
	v_mfma_f32_16x16x4_f32 v[8:11], v66, v22, v[8:11]
	v_mfma_f32_16x16x4_f32 v[12:15], v67, v23, v[12:15]
	v_mfma_f32_16x16x4_f32 v[8:11], v68, v24, v[8:11]
	v_mfma_f32_16x16x4_f32 v[12:15], v69, v25, v[12:15]
	v_mfma_f32_16x16x4_f32 v[8:11], v70, v26, v[8:11]
	v_mfma_f32_16x16x4_f32 v[12:15], v71, v27, v[12:15]
	s_waitcnt vmcnt(18)
	v_lshlrev_b32_e32 v64, 16, v28
	v_and_b32_e32 v65, 0xffff0000, v28
	v_lshlrev_b32_e32 v66, 16, v29
	v_and_b32_e32 v67, 0xffff0000, v29
	v_lshlrev_b32_e32 v68, 16, v30
	v_and_b32_e32 v69, 0xffff0000, v30
	v_lshlrev_b32_e32 v70, 16, v31
	v_and_b32_e32 v71, 0xffff0000, v31
	v_mfma_f32_16x16x4_f32 v[8:11], v64, v32, v[8:11]
	v_mfma_f32_16x16x4_f32 v[12:15], v65, v33, v[12:15]
	v_mfma_f32_16x16x4_f32 v[8:11], v66, v34, v[8:11]
	v_mfma_f32_16x16x4_f32 v[12:15], v67, v35, v[12:15]
	v_mfma_f32_16x16x4_f32 v[8:11], v68, v36, v[8:11]
	v_mfma_f32_16x16x4_f32 v[12:15], v69, v37, v[12:15]
	v_mfma_f32_16x16x4_f32 v[8:11], v70, v38, v[8:11]
	v_mfma_f32_16x16x4_f32 v[12:15], v71, v39, v[12:15]
	s_waitcnt vmcnt(9)
	v_lshlrev_b32_e32 v64, 16, v40
	v_and_b32_e32 v65, 0xffff0000, v40
	v_lshlrev_b32_e32 v66, 16, v41
	v_and_b32_e32 v67, 0xffff0000, v41
	v_lshlrev_b32_e32 v68, 16, v42
	v_and_b32_e32 v69, 0xffff0000, v42
	v_lshlrev_b32_e32 v70, 16, v43
	v_and_b32_e32 v71, 0xffff0000, v43
	v_mfma_f32_16x16x4_f32 v[8:11], v64, v44, v[8:11]
	v_mfma_f32_16x16x4_f32 v[12:15], v65, v45, v[12:15]
	v_mfma_f32_16x16x4_f32 v[8:11], v66, v46, v[8:11]
	v_mfma_f32_16x16x4_f32 v[12:15], v67, v47, v[12:15]
	v_mfma_f32_16x16x4_f32 v[8:11], v68, v48, v[8:11]
	v_mfma_f32_16x16x4_f32 v[12:15], v69, v49, v[12:15]
	v_mfma_f32_16x16x4_f32 v[8:11], v70, v50, v[8:11]
	v_mfma_f32_16x16x4_f32 v[12:15], v71, v51, v[12:15]
	s_waitcnt vmcnt(0)
	v_lshlrev_b32_e32 v64, 16, v52
	v_and_b32_e32 v65, 0xffff0000, v52
	v_lshlrev_b32_e32 v66, 16, v53
	v_and_b32_e32 v67, 0xffff0000, v53
	v_lshlrev_b32_e32 v68, 16, v54
	v_and_b32_e32 v69, 0xffff0000, v54
	v_lshlrev_b32_e32 v70, 16, v55
	v_and_b32_e32 v71, 0xffff0000, v55
	v_mfma_f32_16x16x4_f32 v[8:11], v64, v56, v[8:11]
	v_mfma_f32_16x16x4_f32 v[12:15], v65, v57, v[12:15]
	v_mfma_f32_16x16x4_f32 v[8:11], v66, v58, v[8:11]
	v_mfma_f32_16x16x4_f32 v[12:15], v67, v59, v[12:15]
	v_mfma_f32_16x16x4_f32 v[8:11], v68, v60, v[8:11]
	v_mfma_f32_16x16x4_f32 v[12:15], v69, v61, v[12:15]
	v_mfma_f32_16x16x4_f32 v[8:11], v70, v62, v[8:11]
	v_mfma_f32_16x16x4_f32 v[12:15], v71, v63, v[12:15]
	s_nop 9
	v_add_f32_e32 v8, v8, v12
	v_add_f32_e32 v9, v9, v13
	v_add_f32_e32 v10, v10, v14
	v_add_f32_e32 v11, v11, v15
	s_lshl_b32 s18, s14, 10
	v_add_u32_e32 v73, s18, v72
	global_store_dword v73, v8, s[16:17]
	global_store_dword v73, v9, s[16:17] offset:64
	global_store_dword v73, v10, s[16:17] offset:128
	global_store_dword v73, v11, s[16:17] offset:192
	s_add_i32 s14, s14, s15
	s_branch .Lxa_blk
